# MLA loop: ds_read prefetch depth 6 with 7 rotating buffers (v176-183 freed by switching the stage DMA to SGPR-base + 32-bit offset form)
# speedup vs baseline: 1.0372x; 1.0097x over previous
.LBB0_859:
	ds_read_b128 v[236:239], v214 offset:8192
	ds_read_b128 v[240:243], v215 offset:8192
	ds_read_b128 v[244:247], v216 offset:8192
	ds_read_b128 v[248:251], v217 offset:8192
	ds_read_b128 v[252:255], v218 offset:8192
	ds_read_b128 v[176:179], v219 offset:8192
	v_exp_f32_e32 v97, v97
	v_exp_f32_e32 v99, v99
	v_exp_f32_e32 v100, v100
	v_exp_f32_e32 v101, v101
	v_exp_f32_e32 v102, v102
	v_exp_f32_e32 v103, v103
	v_exp_f32_e32 v106, v106
	v_exp_f32_e32 v107, v107
	s_waitcnt lgkmcnt(5)
	v_mfma_f32_32x32x16_bf16 v[80:95], v[236:239], v[144:147], v[64:79]
	ds_read_b128 v[180:183], v220 offset:8192
	v_exp_f32_e32 v108, v108
	v_exp_f32_e32 v109, v109
	v_exp_f32_e32 v110, v110
	v_exp_f32_e32 v111, v111
	s_waitcnt lgkmcnt(5)
	v_mfma_f32_32x32x16_bf16 v[80:95], v[240:243], v[156:159], v[80:95]
	ds_read_b128 v[236:239], v221 offset:8192
	s_add_u32 s98, s34, s60
	s_addc_u32 s99, s35, s59
	s_add_u32 s98, s98, 0x140fc000
	s_addc_u32 s99, s99, 0
	s_add_u32 s100, s34, s62
	s_addc_u32 s101, s35, s61
	s_add_u32 s100, s100, 0x171b0100
	s_addc_u32 s101, s101, 0
	s_mov_b32 m0, s52
	s_cmp_lg_u64 s[24:25], 0
	s_cselect_b32 s4, s100, s98
	s_cselect_b32 s5, s101, s99
	global_load_lds_dwordx4 v190, s[4:5]
	s_mov_b32 m0, s53
	s_cmp_lg_u64 s[26:27], 0
	s_cselect_b32 s4, s100, s98
	s_cselect_b32 s5, s101, s99
	global_load_lds_dwordx4 v192, s[4:5]
	s_mov_b32 m0, s54
	s_cmp_lg_u64 s[28:29], 0
	s_cselect_b32 s4, s100, s98
	s_cselect_b32 s5, s101, s99
	global_load_lds_dwordx4 v194, s[4:5]
	s_mov_b32 m0, s55
	s_cmp_lg_u64 s[30:31], 0
	s_cselect_b32 s4, s100, s98
	s_cselect_b32 s5, s101, s99
	global_load_lds_dwordx4 v196, s[4:5]
	s_mov_b32 m0, s56
	s_cmp_lg_u64 s[6:7], 0
	s_cselect_b32 s4, s100, s98
	s_cselect_b32 s5, s101, s99
	global_load_lds_dwordx4 v198, s[4:5]
	s_waitcnt lgkmcnt(5)
	v_mfma_f32_32x32x16_bf16 v[80:95], v[244:247], v[168:171], v[80:95]
	ds_read_b128 v[240:243], v205 offset:53248
	s_waitcnt lgkmcnt(5)
	v_mfma_f32_32x32x16_bf16 v[80:95], v[248:251], v[172:175], v[80:95]
	ds_read_b128 v[244:247], v207 offset:53248
	s_waitcnt lgkmcnt(5)
	v_mfma_f32_32x32x16_bf16 v[80:95], v[252:255], v[164:167], v[80:95]
	ds_read_b128 v[248:251], v209 offset:53248
	s_waitcnt lgkmcnt(5)
	v_mfma_f32_32x32x16_bf16 v[80:95], v[176:179], v[160:163], v[80:95]
	ds_read_b128 v[252:255], v211 offset:53248
	s_waitcnt lgkmcnt(5)
	v_mfma_f32_32x32x16_bf16 v[80:95], v[180:183], v[152:155], v[80:95]
	ds_read_b128 v[176:179], v225
	s_waitcnt lgkmcnt(5)
	v_mfma_f32_32x32x16_bf16 v[80:95], v[236:239], v[148:151], v[80:95]
	ds_read_b128 v[180:183], v225 offset:4096
	s_waitcnt lgkmcnt(5)
	v_mfma_f32_32x32x16_bf16 v[80:95], v[240:243], v[140:143], v[80:95]
	ds_read_b128 v[236:239], v225 offset:8192
	s_waitcnt lgkmcnt(5)
	v_mfma_f32_32x32x16_bf16 v[80:95], v[244:247], v[136:139], v[80:95]
	ds_read_b128 v[240:243], v225 offset:12288
	s_waitcnt lgkmcnt(5)
	v_mfma_f32_32x32x16_bf16 v[80:95], v[248:251], v[132:135], v[80:95]
	ds_read_b128 v[244:247], v226
	s_waitcnt lgkmcnt(5)
	v_mfma_f32_32x32x16_bf16 v[80:95], v[252:255], v[128:131], v[80:95]
	ds_read_b128 v[248:251], v226 offset:4096
	v_exp_f32_e32 v112, v96
	v_exp_f32_e32 v113, v98
	v_exp_f32_e32 v114, v104
	v_exp_f32_e32 v115, v105
	v_add_f32_e32 v96, 0, v112
	v_add_f32_e32 v96, v97, v96
	v_add_f32_e32 v96, v113, v96
	v_add_f32_e32 v96, v99, v96
	v_add_f32_e32 v96, v100, v96
	v_add_f32_e32 v96, v101, v96
	v_add_f32_e32 v96, v102, v96
	v_add_f32_e32 v96, v103, v96
	v_cvt_pk_bf16_f32 v100, v100, v101
	v_cvt_pk_bf16_f32 v101, v102, v103
	v_cvt_pk_bf16_f32 v98, v112, v97
	v_cvt_pk_bf16_f32 v99, v113, v99
	v_max_f32_e32 v97, v81, v81
	v_add_f32_e32 v96, v114, v96
	s_waitcnt lgkmcnt(5)
	v_mfma_f32_32x32x16_bf16 v[48:63], v[176:179], v[98:101], v[48:63]
	ds_read_b128 v[252:255], v226 offset:8192
	v_add_f32_e32 v96, v115, v96
	v_add_f32_e32 v96, v106, v96
	v_add_f32_e32 v96, v107, v96
	v_add_f32_e32 v96, v108, v96
	v_add_f32_e32 v96, v109, v96
	v_add_f32_e32 v96, v110, v96
	s_waitcnt lgkmcnt(5)
	v_mfma_f32_32x32x16_bf16 v[32:47], v[180:183], v[98:101], v[32:47]
	ds_read_b128 v[176:179], v226 offset:12288
	v_add_f32_e32 v96, v111, v96
	v_add_f32_e32 v112, v230, v96
	s_waitcnt lgkmcnt(5)
	v_mfma_f32_32x32x16_bf16 v[16:31], v[236:239], v[98:101], v[16:31]
	ds_read_b128 v[180:183], v214 offset:16384
	s_waitcnt lgkmcnt(5)
	v_mfma_f32_32x32x16_bf16 v[0:15], v[240:243], v[98:101], v[0:15]
	ds_read_b128 v[236:239], v215 offset:16384
	v_cvt_pk_bf16_f32 v98, v114, v115
	v_cvt_pk_bf16_f32 v99, v106, v107
	v_cvt_pk_bf16_f32 v100, v108, v109
	v_cvt_pk_bf16_f32 v101, v110, v111
	s_nop 0
	s_waitcnt lgkmcnt(5)
	v_mfma_f32_32x32x16_bf16 v[48:63], v[244:247], v[98:101], v[48:63]
	ds_read_b128 v[240:243], v216 offset:16384
	s_waitcnt lgkmcnt(5)
	v_mfma_f32_32x32x16_bf16 v[32:47], v[248:251], v[98:101], v[32:47]
	ds_read_b128 v[244:247], v217 offset:16384
	s_waitcnt lgkmcnt(5)
	v_mfma_f32_32x32x16_bf16 v[16:31], v[252:255], v[98:101], v[16:31]
	ds_read_b128 v[248:251], v218 offset:16384
	s_waitcnt lgkmcnt(5)
	v_mfma_f32_32x32x16_bf16 v[0:15], v[176:179], v[98:101], v[0:15]
	ds_read_b128 v[252:255], v219 offset:16384
	v_max_f32_e32 v98, v80, v80
	v_max_f32_e32 v97, v98, v97
	v_max3_f32 v97, v97, v82, v83
	v_max3_f32 v97, v97, v84, v85
	v_max3_f32 v97, v97, v86, v87
	v_max3_f32 v97, v97, v88, v89
	v_max3_f32 v97, v97, v90, v91
	v_max3_f32 v97, v97, v92, v93
	v_max3_f32 v97, v97, v94, v95
	ds_bpermute_b32 v98, v229, v97
	s_waitcnt lgkmcnt(0)
	v_max_f32_e32 v96, v98, v98
	v_max_f32_e32 v96, v97, v96
	v_cmp_lt_f32_e32 vcc, 0, v96
	s_cbranch_vccz .LBB0_861
	v_max_f32_e32 v96, v96, v96
	v_max_f32_e32 v96, 0, v96
	v_exp_f32_e64 v98, -v96
	v_pk_add_f32 v[80:81], v[80:81], v[96:97] op_sel_hi:[1,0] neg_lo:[0,1] neg_hi:[0,1]
	v_pk_add_f32 v[82:83], v[82:83], v[96:97] op_sel_hi:[1,0] neg_lo:[0,1] neg_hi:[0,1]
	v_pk_add_f32 v[84:85], v[84:85], v[96:97] op_sel_hi:[1,0] neg_lo:[0,1] neg_hi:[0,1]
	v_mul_f32_e32 v112, v112, v98
	v_pk_add_f32 v[86:87], v[86:87], v[96:97] op_sel_hi:[1,0] neg_lo:[0,1] neg_hi:[0,1]
	v_pk_add_f32 v[88:89], v[88:89], v[96:97] op_sel_hi:[1,0] neg_lo:[0,1] neg_hi:[0,1]
	v_pk_add_f32 v[90:91], v[90:91], v[96:97] op_sel_hi:[1,0] neg_lo:[0,1] neg_hi:[0,1]
	v_pk_add_f32 v[92:93], v[92:93], v[96:97] op_sel_hi:[1,0] neg_lo:[0,1] neg_hi:[0,1]
	v_sub_f32_e32 v79, v79, v96
	v_sub_f32_e32 v78, v78, v96
	v_sub_f32_e32 v77, v77, v96
	v_sub_f32_e32 v76, v76, v96
	v_sub_f32_e32 v75, v75, v96
	v_sub_f32_e32 v74, v74, v96
	v_sub_f32_e32 v73, v73, v96
	v_sub_f32_e32 v72, v72, v96
	v_sub_f32_e32 v71, v71, v96
	v_sub_f32_e32 v70, v70, v96
	v_sub_f32_e32 v69, v69, v96
	v_sub_f32_e32 v68, v68, v96
	v_sub_f32_e32 v67, v67, v96
	v_sub_f32_e32 v66, v66, v96
	v_sub_f32_e32 v65, v65, v96
	v_sub_f32_e32 v64, v64, v96
	v_pk_add_f32 v[94:95], v[94:95], v[96:97] op_sel_hi:[1,0] neg_lo:[0,1] neg_hi:[0,1]
	v_pk_mul_f32 v[62:63], v[62:63], v[98:99] op_sel_hi:[1,0]
	v_pk_mul_f32 v[60:61], v[60:61], v[98:99] op_sel_hi:[1,0]
	v_pk_mul_f32 v[58:59], v[58:59], v[98:99] op_sel_hi:[1,0]
	v_pk_mul_f32 v[56:57], v[56:57], v[98:99] op_sel_hi:[1,0]
	v_pk_mul_f32 v[54:55], v[54:55], v[98:99] op_sel_hi:[1,0]
	v_pk_mul_f32 v[52:53], v[52:53], v[98:99] op_sel_hi:[1,0]
	v_pk_mul_f32 v[50:51], v[50:51], v[98:99] op_sel_hi:[1,0]
	v_pk_mul_f32 v[48:49], v[48:49], v[98:99] op_sel_hi:[1,0]
	v_pk_mul_f32 v[46:47], v[46:47], v[98:99] op_sel_hi:[1,0]
	v_pk_mul_f32 v[44:45], v[44:45], v[98:99] op_sel_hi:[1,0]
	v_pk_mul_f32 v[42:43], v[42:43], v[98:99] op_sel_hi:[1,0]
	v_pk_mul_f32 v[40:41], v[40:41], v[98:99] op_sel_hi:[1,0]
	v_pk_mul_f32 v[38:39], v[38:39], v[98:99] op_sel_hi:[1,0]
	v_pk_mul_f32 v[36:37], v[36:37], v[98:99] op_sel_hi:[1,0]
	v_pk_mul_f32 v[34:35], v[34:35], v[98:99] op_sel_hi:[1,0]
	v_pk_mul_f32 v[32:33], v[32:33], v[98:99] op_sel_hi:[1,0]
	v_pk_mul_f32 v[30:31], v[30:31], v[98:99] op_sel_hi:[1,0]
	v_pk_mul_f32 v[28:29], v[28:29], v[98:99] op_sel_hi:[1,0]
	v_pk_mul_f32 v[26:27], v[26:27], v[98:99] op_sel_hi:[1,0]
	v_pk_mul_f32 v[24:25], v[24:25], v[98:99] op_sel_hi:[1,0]
	v_pk_mul_f32 v[22:23], v[22:23], v[98:99] op_sel_hi:[1,0]
	v_pk_mul_f32 v[20:21], v[20:21], v[98:99] op_sel_hi:[1,0]
	v_pk_mul_f32 v[18:19], v[18:19], v[98:99] op_sel_hi:[1,0]
	v_pk_mul_f32 v[16:17], v[16:17], v[98:99] op_sel_hi:[1,0]
	v_pk_mul_f32 v[14:15], v[14:15], v[98:99] op_sel_hi:[1,0]
	v_pk_mul_f32 v[12:13], v[12:13], v[98:99] op_sel_hi:[1,0]
	v_pk_mul_f32 v[10:11], v[10:11], v[98:99] op_sel_hi:[1,0]
	v_pk_mul_f32 v[8:9], v[8:9], v[98:99] op_sel_hi:[1,0]
	v_pk_mul_f32 v[6:7], v[6:7], v[98:99] op_sel_hi:[1,0]
	v_pk_mul_f32 v[4:5], v[4:5], v[98:99] op_sel_hi:[1,0]
	v_pk_mul_f32 v[2:3], v[2:3], v[98:99] op_sel_hi:[1,0]
	v_pk_mul_f32 v[0:1], v[0:1], v[98:99] op_sel_hi:[1,0]
.LBB0_861:
	v_exp_f32_e32 v113, v80
	v_exp_f32_e32 v122, v81
	v_exp_f32_e32 v123, v82
	v_mfma_f32_32x32x16_bf16 v[96:111], v[180:183], v[144:147], v[64:79]
	ds_read_b128 v[176:179], v220 offset:16384
	v_exp_f32_e32 v124, v83
	v_exp_f32_e32 v125, v84
	v_exp_f32_e32 v126, v85
	v_exp_f32_e32 v127, v86
	v_exp_f32_e32 v230, v87
	v_exp_f32_e32 v88, v88
	v_exp_f32_e32 v89, v89
	v_mfma_f32_32x32x16_bf16 v[96:111], v[236:239], v[156:159], v[96:111]
	ds_read_b128 v[180:183], v221 offset:16384
	v_exp_f32_e32 v90, v90
	v_exp_f32_e32 v91, v91
	v_exp_f32_e32 v92, v92
	v_exp_f32_e32 v93, v93
	v_exp_f32_e32 v94, v94
	v_exp_f32_e32 v95, v95
	v_mfma_f32_32x32x16_bf16 v[96:111], v[240:243], v[168:171], v[96:111]
	ds_read_b128 v[236:239], v205 offset:57344
	v_mfma_f32_32x32x16_bf16 v[96:111], v[244:247], v[172:175], v[96:111]
	ds_read_b128 v[240:243], v207 offset:57344
	v_mfma_f32_32x32x16_bf16 v[96:111], v[248:251], v[164:167], v[96:111]
	ds_read_b128 v[244:247], v209 offset:57344
	v_mfma_f32_32x32x16_bf16 v[96:111], v[252:255], v[160:163], v[96:111]
	ds_read_b128 v[248:251], v211 offset:57344
	s_waitcnt lgkmcnt(5)
	v_mfma_f32_32x32x16_bf16 v[96:111], v[176:179], v[152:155], v[96:111]
	ds_read_b128 v[252:255], v227
	s_waitcnt lgkmcnt(5)
	v_mfma_f32_32x32x16_bf16 v[96:111], v[180:183], v[148:151], v[96:111]
	ds_read_b128 v[176:179], v227 offset:4096
	s_waitcnt lgkmcnt(5)
	v_mfma_f32_32x32x16_bf16 v[96:111], v[236:239], v[140:143], v[96:111]
	ds_read_b128 v[180:183], v227 offset:8192
	s_waitcnt lgkmcnt(5)
	v_mfma_f32_32x32x16_bf16 v[96:111], v[240:243], v[136:139], v[96:111]
	ds_read_b128 v[236:239], v227 offset:12288
	s_waitcnt lgkmcnt(5)
	v_mfma_f32_32x32x16_bf16 v[96:111], v[244:247], v[132:135], v[96:111]
	ds_read_b128 v[240:243], v228 offset:4096
	v_cvt_pk_bf16_f32 v114, v113, v122
	v_cvt_pk_bf16_f32 v115, v123, v124
	v_cvt_pk_bf16_f32 v116, v125, v126
	v_cvt_pk_bf16_f32 v117, v127, v230
	s_waitcnt lgkmcnt(5)
	v_mfma_f32_32x32x16_bf16 v[96:111], v[248:251], v[128:131], v[96:111]
	ds_read_b128 v[244:247], v228
	v_add_f32_e32 v118, 0, v113
	v_add_f32_e32 v113, v122, v118
	v_add_f32_e32 v113, v123, v113
	s_waitcnt lgkmcnt(5)
	v_mfma_f32_32x32x16_bf16 v[48:63], v[252:255], v[114:117], v[48:63]
	ds_read_b128 v[248:251], v228 offset:8192
	v_add_f32_e32 v80, v124, v113
	v_add_f32_e32 v80, v125, v80
	v_add_f32_e32 v80, v126, v80
	v_add_f32_e32 v113, v127, v80
	s_waitcnt lgkmcnt(5)
	v_mfma_f32_32x32x16_bf16 v[32:47], v[176:179], v[114:117], v[32:47]
	ds_read_b128 v[252:255], v228 offset:12288
	v_add_f32_e32 v84, v230, v113
	v_add_f32_e32 v84, v88, v84
	v_add_f32_e32 v113, v89, v84
	s_waitcnt lgkmcnt(5)
	v_mfma_f32_32x32x16_bf16 v[16:31], v[180:183], v[114:117], v[16:31]
	ds_read_b128 v[176:179], v214 offset:24576
	v_add_f32_e32 v80, v90, v113
	v_add_f32_e32 v80, v91, v80
	v_add_f32_e32 v80, v92, v80
	v_add_f32_e32 v113, v93, v80
	v_add_f32_e32 v113, v94, v113
	s_waitcnt lgkmcnt(5)
	v_mfma_f32_32x32x16_bf16 v[0:15], v[236:239], v[114:117], v[0:15]
	ds_read_b128 v[180:183], v215 offset:24576
	v_cvt_pk_bf16_f32 v84, v88, v89
	v_cvt_pk_bf16_f32 v85, v90, v91
	v_cvt_pk_bf16_f32 v86, v92, v93
	v_max_f32_e32 v92, v97, v97
	v_max_f32_e32 v93, v96, v96
	v_max_f32_e32 v92, v93, v92
	v_max3_f32 v92, v92, v98, v99
	v_max3_f32 v92, v92, v100, v101
	v_cvt_pk_bf16_f32 v87, v94, v95
	v_max3_f32 v92, v92, v102, v103
	v_add_f32_e32 v94, v95, v113
	s_waitcnt lgkmcnt(5)
	v_mfma_f32_32x32x16_bf16 v[32:47], v[240:243], v[84:87], v[32:47]
	ds_read_b128 v[236:239], v216 offset:24576
	v_max3_f32 v88, v92, v104, v105
	v_max3_f32 v88, v88, v106, v107
	v_max3_f32 v88, v88, v108, v109
	v_max3_f32 v92, v88, v110, v111
	ds_bpermute_b32 v93, v229, v92
	v_add_f32_e32 v112, v112, v94
	s_waitcnt lgkmcnt(6)
	v_mfma_f32_32x32x16_bf16 v[48:63], v[244:247], v[84:87], v[48:63]
	ds_read_b128 v[240:243], v217 offset:24576
	s_waitcnt vmcnt(0)
	s_barrier
	s_waitcnt lgkmcnt(6)
	v_mfma_f32_32x32x16_bf16 v[16:31], v[248:251], v[84:87], v[16:31]
	ds_read_b128 v[244:247], v218 offset:24576
	s_waitcnt lgkmcnt(2)
	v_max_f32_e32 v80, v93, v93
	v_max_f32_e32 v80, v92, v80
	v_cmp_lt_f32_e32 vcc, 0, v80
	v_mfma_f32_32x32x16_bf16 v[0:15], v[252:255], v[84:87], v[0:15]
	ds_read_b128 v[248:251], v219 offset:24576
	s_cbranch_vccz .LBB0_863
	v_max_f32_e32 v80, v80, v80
	v_max_f32_e32 v80, 0, v80
	v_exp_f32_e64 v82, -v80
	v_pk_add_f32 v[96:97], v[96:97], v[80:81] op_sel_hi:[1,0] neg_lo:[0,1] neg_hi:[0,1]
	v_pk_add_f32 v[98:99], v[98:99], v[80:81] op_sel_hi:[1,0] neg_lo:[0,1] neg_hi:[0,1]
	v_pk_add_f32 v[100:101], v[100:101], v[80:81] op_sel_hi:[1,0] neg_lo:[0,1] neg_hi:[0,1]
	v_mul_f32_e32 v112, v112, v82
	v_pk_add_f32 v[102:103], v[102:103], v[80:81] op_sel_hi:[1,0] neg_lo:[0,1] neg_hi:[0,1]
	v_pk_add_f32 v[104:105], v[104:105], v[80:81] op_sel_hi:[1,0] neg_lo:[0,1] neg_hi:[0,1]
	v_pk_add_f32 v[106:107], v[106:107], v[80:81] op_sel_hi:[1,0] neg_lo:[0,1] neg_hi:[0,1]
	v_pk_add_f32 v[108:109], v[108:109], v[80:81] op_sel_hi:[1,0] neg_lo:[0,1] neg_hi:[0,1]
	v_sub_f32_e32 v79, v79, v80
	v_sub_f32_e32 v78, v78, v80
	v_sub_f32_e32 v77, v77, v80
	v_sub_f32_e32 v76, v76, v80
	v_sub_f32_e32 v75, v75, v80
	v_sub_f32_e32 v74, v74, v80
	v_sub_f32_e32 v73, v73, v80
	v_sub_f32_e32 v72, v72, v80
	v_sub_f32_e32 v71, v71, v80
	v_sub_f32_e32 v70, v70, v80
	v_sub_f32_e32 v69, v69, v80
	v_sub_f32_e32 v68, v68, v80
	v_sub_f32_e32 v67, v67, v80
	v_sub_f32_e32 v66, v66, v80
	v_sub_f32_e32 v65, v65, v80
	v_sub_f32_e32 v64, v64, v80
	v_pk_add_f32 v[110:111], v[110:111], v[80:81] op_sel_hi:[1,0] neg_lo:[0,1] neg_hi:[0,1]
	v_pk_mul_f32 v[62:63], v[62:63], v[82:83] op_sel_hi:[1,0]
	v_pk_mul_f32 v[60:61], v[60:61], v[82:83] op_sel_hi:[1,0]
	v_pk_mul_f32 v[58:59], v[58:59], v[82:83] op_sel_hi:[1,0]
	v_pk_mul_f32 v[56:57], v[56:57], v[82:83] op_sel_hi:[1,0]
	v_pk_mul_f32 v[54:55], v[54:55], v[82:83] op_sel_hi:[1,0]
	v_pk_mul_f32 v[52:53], v[52:53], v[82:83] op_sel_hi:[1,0]
	v_pk_mul_f32 v[50:51], v[50:51], v[82:83] op_sel_hi:[1,0]
	v_pk_mul_f32 v[48:49], v[48:49], v[82:83] op_sel_hi:[1,0]
	v_pk_mul_f32 v[46:47], v[46:47], v[82:83] op_sel_hi:[1,0]
	v_pk_mul_f32 v[44:45], v[44:45], v[82:83] op_sel_hi:[1,0]
	v_pk_mul_f32 v[42:43], v[42:43], v[82:83] op_sel_hi:[1,0]
	v_pk_mul_f32 v[40:41], v[40:41], v[82:83] op_sel_hi:[1,0]
	v_pk_mul_f32 v[38:39], v[38:39], v[82:83] op_sel_hi:[1,0]
	v_pk_mul_f32 v[36:37], v[36:37], v[82:83] op_sel_hi:[1,0]
	v_pk_mul_f32 v[34:35], v[34:35], v[82:83] op_sel_hi:[1,0]
	v_pk_mul_f32 v[32:33], v[32:33], v[82:83] op_sel_hi:[1,0]
	v_pk_mul_f32 v[30:31], v[30:31], v[82:83] op_sel_hi:[1,0]
	v_pk_mul_f32 v[28:29], v[28:29], v[82:83] op_sel_hi:[1,0]
	v_pk_mul_f32 v[26:27], v[26:27], v[82:83] op_sel_hi:[1,0]
	v_pk_mul_f32 v[24:25], v[24:25], v[82:83] op_sel_hi:[1,0]
	v_pk_mul_f32 v[22:23], v[22:23], v[82:83] op_sel_hi:[1,0]
	v_pk_mul_f32 v[20:21], v[20:21], v[82:83] op_sel_hi:[1,0]
	v_pk_mul_f32 v[18:19], v[18:19], v[82:83] op_sel_hi:[1,0]
	v_pk_mul_f32 v[16:17], v[16:17], v[82:83] op_sel_hi:[1,0]
	v_pk_mul_f32 v[14:15], v[14:15], v[82:83] op_sel_hi:[1,0]
	v_pk_mul_f32 v[12:13], v[12:13], v[82:83] op_sel_hi:[1,0]
	v_pk_mul_f32 v[10:11], v[10:11], v[82:83] op_sel_hi:[1,0]
	v_pk_mul_f32 v[8:9], v[8:9], v[82:83] op_sel_hi:[1,0]
	v_pk_mul_f32 v[6:7], v[6:7], v[82:83] op_sel_hi:[1,0]
	v_pk_mul_f32 v[4:5], v[4:5], v[82:83] op_sel_hi:[1,0]
	v_pk_mul_f32 v[2:3], v[2:3], v[82:83] op_sel_hi:[1,0]
	v_pk_mul_f32 v[0:1], v[0:1], v[82:83] op_sel_hi:[1,0]
.LBB0_863:
	v_exp_f32_e32 v96, v96
	v_exp_f32_e32 v97, v97
	v_exp_f32_e32 v98, v98
	v_mfma_f32_32x32x16_bf16 v[80:95], v[176:179], v[144:147], v[64:79]
	ds_read_b128 v[252:255], v220 offset:24576
	v_exp_f32_e32 v99, v99
	v_exp_f32_e32 v100, v100
	v_exp_f32_e32 v101, v101
	v_exp_f32_e32 v102, v102
	v_exp_f32_e32 v103, v103
	v_cvt_pk_bf16_f32 v122, v96, v97
	v_cvt_pk_bf16_f32 v123, v98, v99
	v_mfma_f32_32x32x16_bf16 v[80:95], v[180:183], v[156:159], v[80:95]
	ds_read_b128 v[176:179], v221 offset:24576
	s_add_i32 s4, s8, 3
	s_cmp_ge_u32 s4, s9
	s_cbranch_scc1 .Lmla_dma_skip_t1
	s_add_u32 s98, s34, s60
	s_addc_u32 s99, s35, s59
	s_add_u32 s98, s98, 0x14102000
	s_addc_u32 s99, s99, 0
	s_add_u32 s100, s34, s62
	s_addc_u32 s101, s35, s61
	s_add_u32 s100, s100, 0x171b0180
	s_addc_u32 s101, s101, 0
	s_mov_b32 m0, s41
	s_cmp_lg_u64 s[24:25], 0
	s_cselect_b32 s4, s100, s98
	s_cselect_b32 s5, s101, s99
	global_load_lds_dwordx4 v190, s[4:5]
	s_mov_b32 m0, s42
	s_cmp_lg_u64 s[26:27], 0
	s_cselect_b32 s4, s100, s98
	s_cselect_b32 s5, s101, s99
	global_load_lds_dwordx4 v192, s[4:5]
	s_mov_b32 m0, s43
	s_cmp_lg_u64 s[28:29], 0
	s_cselect_b32 s4, s100, s98
	s_cselect_b32 s5, s101, s99
	global_load_lds_dwordx4 v194, s[4:5]
	s_mov_b32 m0, s44
	s_cmp_lg_u64 s[30:31], 0
	s_cselect_b32 s4, s100, s98
	s_cselect_b32 s5, s101, s99
	global_load_lds_dwordx4 v196, s[4:5]
	s_mov_b32 m0, s45
	s_cmp_lg_u64 s[6:7], 0
	s_cselect_b32 s4, s100, s98
	s_cselect_b32 s5, s101, s99
	global_load_lds_dwordx4 v198, s[4:5]
.Lmla_dma_skip_t1:
	v_cvt_pk_bf16_f32 v124, v100, v101
	v_cvt_pk_bf16_f32 v125, v102, v103
	v_exp_f32_e32 v104, v104
	v_exp_f32_e32 v105, v105
	v_exp_f32_e32 v106, v106
	v_exp_f32_e32 v107, v107
	v_mfma_f32_32x32x16_bf16 v[80:95], v[236:239], v[168:171], v[80:95]
	ds_read_b128 v[180:183], v205 offset:61440
	v_exp_f32_e32 v108, v108
	v_exp_f32_e32 v109, v109
	v_exp_f32_e32 v110, v110
	v_exp_f32_e32 v111, v111
	s_add_i32 s16, s8, 3
	s_cmp_lt_u32 s16, s9
	s_cselect_b64 s[10:11], -1, 0
	s_waitcnt lgkmcnt(5)
	v_mfma_f32_32x32x16_bf16 v[80:95], v[240:243], v[172:175], v[80:95]
	ds_read_b128 v[236:239], v207 offset:61440
	s_cmp_ge_u32 s16, s9
	s_waitcnt lgkmcnt(5)
	v_mfma_f32_32x32x16_bf16 v[80:95], v[244:247], v[164:167], v[80:95]
	ds_read_b128 v[240:243], v209 offset:61440
	s_waitcnt lgkmcnt(5)
	v_mfma_f32_32x32x16_bf16 v[80:95], v[248:251], v[160:163], v[80:95]
	ds_read_b128 v[244:247], v211 offset:61440
	s_waitcnt lgkmcnt(5)
	v_mfma_f32_32x32x16_bf16 v[80:95], v[252:255], v[152:155], v[80:95]
	ds_read_b128 v[248:251], v225 offset:16384
	s_waitcnt lgkmcnt(5)
	v_mfma_f32_32x32x16_bf16 v[80:95], v[176:179], v[148:151], v[80:95]
	ds_read_b128 v[252:255], v225 offset:20480
	s_waitcnt lgkmcnt(5)
	v_mfma_f32_32x32x16_bf16 v[80:95], v[180:183], v[140:143], v[80:95]
	ds_read_b128 v[176:179], v225 offset:24576
	s_waitcnt lgkmcnt(5)
	v_mfma_f32_32x32x16_bf16 v[80:95], v[236:239], v[136:139], v[80:95]
	ds_read_b128 v[180:183], v225 offset:28672
	s_waitcnt lgkmcnt(5)
	v_mfma_f32_32x32x16_bf16 v[80:95], v[240:243], v[132:135], v[80:95]
	ds_read_b128 v[236:239], v226 offset:16384
	s_waitcnt lgkmcnt(5)
	v_mfma_f32_32x32x16_bf16 v[80:95], v[244:247], v[128:131], v[80:95]
	ds_read_b128 v[240:243], v226 offset:20480
	s_waitcnt lgkmcnt(5)
	v_mfma_f32_32x32x16_bf16 v[48:63], v[248:251], v[122:125], v[48:63]
	ds_read_b128 v[244:247], v226 offset:24576
	s_nop 8
	v_max_f32_e32 v113, v81, v81
	v_max_f32_e32 v126, v80, v80
	v_max_f32_e32 v113, v126, v113
	v_max3_f32 v113, v113, v82, v83
	v_max3_f32 v113, v113, v84, v85
	v_max3_f32 v113, v113, v86, v87
	v_max3_f32 v113, v113, v88, v89
	s_waitcnt lgkmcnt(5)
	v_mfma_f32_32x32x16_bf16 v[32:47], v[252:255], v[122:125], v[32:47]
	ds_read_b128 v[248:251], v226 offset:28672
	v_max3_f32 v113, v113, v90, v91
	v_max3_f32 v113, v113, v92, v93
	v_max3_f32 v113, v113, v94, v95
	s_waitcnt lgkmcnt(5)
	v_mfma_f32_32x32x16_bf16 v[16:31], v[176:179], v[122:125], v[16:31]
	ds_read_b128 v[252:255], v214 offset:32768
	s_waitcnt lgkmcnt(5)
	v_mfma_f32_32x32x16_bf16 v[0:15], v[180:183], v[122:125], v[0:15]
	ds_read_b128 v[176:179], v215 offset:32768
	v_cvt_pk_bf16_f32 v118, v104, v105
	v_cvt_pk_bf16_f32 v119, v106, v107
	v_cvt_pk_bf16_f32 v120, v108, v109
	v_cvt_pk_bf16_f32 v121, v110, v111
	s_nop 0
	s_waitcnt lgkmcnt(5)
	v_mfma_f32_32x32x16_bf16 v[48:63], v[236:239], v[118:121], v[48:63]
	ds_read_b128 v[180:183], v216 offset:32768
	s_waitcnt lgkmcnt(5)
	v_mfma_f32_32x32x16_bf16 v[32:47], v[240:243], v[118:121], v[32:47]
	ds_read_b128 v[236:239], v217 offset:32768
	s_waitcnt lgkmcnt(5)
	v_mfma_f32_32x32x16_bf16 v[16:31], v[244:247], v[118:121], v[16:31]
	ds_read_b128 v[240:243], v218 offset:32768
	ds_bpermute_b32 v114, v229, v113
	s_waitcnt lgkmcnt(6)
	v_mfma_f32_32x32x16_bf16 v[0:15], v[248:251], v[118:121], v[0:15]
	ds_read_b128 v[244:247], v219 offset:32768

.LBB0_867:
	v_exp_f32_e32 v113, v80
	v_exp_f32_e32 v122, v81
	v_exp_f32_e32 v123, v82
	v_mfma_f32_32x32x16_bf16 v[96:111], v[252:255], v[144:147], v[64:79]
	ds_read_b128 v[248:251], v220 offset:32768
	v_exp_f32_e32 v124, v83
	v_exp_f32_e32 v125, v84
	v_exp_f32_e32 v126, v85
	v_exp_f32_e32 v127, v86
	v_exp_f32_e32 v230, v87
	v_exp_f32_e32 v88, v88
	v_exp_f32_e32 v89, v89
	v_mfma_f32_32x32x16_bf16 v[96:111], v[176:179], v[156:159], v[96:111]
	ds_read_b128 v[252:255], v221 offset:32768
	v_exp_f32_e32 v90, v90
	v_exp_f32_e32 v91, v91
	v_exp_f32_e32 v92, v92
	v_exp_f32_e32 v93, v93
	v_exp_f32_e32 v94, v94
	v_exp_f32_e32 v95, v95
	v_mfma_f32_32x32x16_bf16 v[96:111], v[180:183], v[168:171], v[96:111]
	ds_read_b128 v[176:179], v206 offset:16384
	v_mfma_f32_32x32x16_bf16 v[96:111], v[236:239], v[172:175], v[96:111]
	ds_read_b128 v[180:183], v208 offset:16384
	v_mfma_f32_32x32x16_bf16 v[96:111], v[240:243], v[164:167], v[96:111]
	ds_read_b128 v[236:239], v210 offset:16384
	s_waitcnt lgkmcnt(5)
	v_mfma_f32_32x32x16_bf16 v[96:111], v[244:247], v[160:163], v[96:111]
	ds_read_b128 v[240:243], v212 offset:16384
	s_waitcnt lgkmcnt(5)
	v_mfma_f32_32x32x16_bf16 v[96:111], v[248:251], v[152:155], v[96:111]
	ds_read_b128 v[244:247], v227 offset:16384
	s_waitcnt lgkmcnt(5)
	v_mfma_f32_32x32x16_bf16 v[96:111], v[252:255], v[148:151], v[96:111]
	ds_read_b128 v[248:251], v227 offset:20480
	s_waitcnt lgkmcnt(5)
	v_mfma_f32_32x32x16_bf16 v[96:111], v[176:179], v[140:143], v[96:111]
	ds_read_b128 v[252:255], v227 offset:24576
	s_waitcnt lgkmcnt(5)
	v_mfma_f32_32x32x16_bf16 v[96:111], v[180:183], v[136:139], v[96:111]
	ds_read_b128 v[176:179], v227 offset:28672
	s_waitcnt lgkmcnt(5)
	v_mfma_f32_32x32x16_bf16 v[96:111], v[236:239], v[132:135], v[96:111]
	ds_read_b128 v[180:183], v228 offset:20480
	v_cvt_pk_bf16_f32 v114, v113, v122
	v_cvt_pk_bf16_f32 v115, v123, v124
	v_cvt_pk_bf16_f32 v116, v125, v126
	v_cvt_pk_bf16_f32 v117, v127, v230
	s_waitcnt lgkmcnt(5)
	v_mfma_f32_32x32x16_bf16 v[96:111], v[240:243], v[128:131], v[96:111]
	ds_read_b128 v[236:239], v228 offset:16384
	v_add_f32_e32 v118, 0, v113
	v_add_f32_e32 v113, v122, v118
	v_add_f32_e32 v113, v123, v113
	s_waitcnt lgkmcnt(5)
	v_mfma_f32_32x32x16_bf16 v[48:63], v[244:247], v[114:117], v[48:63]
	ds_read_b128 v[240:243], v228 offset:24576
	v_add_f32_e32 v80, v124, v113
	v_add_f32_e32 v80, v125, v80
	v_add_f32_e32 v80, v126, v80
	v_add_f32_e32 v113, v127, v80
	s_waitcnt lgkmcnt(5)
	v_mfma_f32_32x32x16_bf16 v[32:47], v[248:251], v[114:117], v[32:47]
	ds_read_b128 v[244:247], v228 offset:28672
	v_add_f32_e32 v84, v230, v113
	v_add_f32_e32 v84, v88, v84
	v_add_f32_e32 v113, v89, v84
	s_waitcnt lgkmcnt(5)
	v_mfma_f32_32x32x16_bf16 v[16:31], v[252:255], v[114:117], v[16:31]
	ds_read_b128 v[248:251], v214 offset:40960
	v_add_f32_e32 v80, v90, v113
	v_add_f32_e32 v80, v91, v80
	v_add_f32_e32 v80, v92, v80
	v_add_f32_e32 v113, v93, v80
	v_add_f32_e32 v113, v94, v113
	s_waitcnt lgkmcnt(5)
	v_mfma_f32_32x32x16_bf16 v[0:15], v[176:179], v[114:117], v[0:15]
	ds_read_b128 v[252:255], v215 offset:40960
	v_cvt_pk_bf16_f32 v84, v88, v89
	v_cvt_pk_bf16_f32 v85, v90, v91
	v_cvt_pk_bf16_f32 v86, v92, v93
	v_max_f32_e32 v92, v97, v97
	v_max_f32_e32 v93, v96, v96
	v_max_f32_e32 v92, v93, v92
	v_max3_f32 v92, v92, v98, v99
	v_max3_f32 v92, v92, v100, v101
	v_cvt_pk_bf16_f32 v87, v94, v95
	v_max3_f32 v92, v92, v102, v103
	v_add_f32_e32 v94, v95, v113
	s_waitcnt lgkmcnt(5)
	v_mfma_f32_32x32x16_bf16 v[32:47], v[180:183], v[84:87], v[32:47]
	ds_read_b128 v[176:179], v216 offset:40960
	v_max3_f32 v88, v92, v104, v105
	v_max3_f32 v88, v88, v106, v107
	v_max3_f32 v88, v88, v108, v109
	v_max3_f32 v92, v88, v110, v111
	ds_bpermute_b32 v93, v229, v92
	v_add_f32_e32 v112, v112, v94
	s_waitcnt lgkmcnt(6)
	v_mfma_f32_32x32x16_bf16 v[48:63], v[236:239], v[84:87], v[48:63]
	ds_read_b128 v[180:183], v217 offset:40960
	s_waitcnt vmcnt(0)
	s_barrier
	s_waitcnt lgkmcnt(6)
	v_mfma_f32_32x32x16_bf16 v[16:31], v[240:243], v[84:87], v[16:31]
	ds_read_b128 v[236:239], v218 offset:40960
	s_waitcnt lgkmcnt(2)
	v_max_f32_e32 v80, v93, v93
	v_max_f32_e32 v80, v92, v80
	v_cmp_lt_f32_e32 vcc, 0, v80
	v_mfma_f32_32x32x16_bf16 v[0:15], v[244:247], v[84:87], v[0:15]
	ds_read_b128 v[240:243], v219 offset:40960
	s_cbranch_vccz .LBB0_869
	v_max_f32_e32 v80, v80, v80
	v_max_f32_e32 v80, 0, v80
	v_exp_f32_e64 v82, -v80
	v_pk_add_f32 v[96:97], v[96:97], v[80:81] op_sel_hi:[1,0] neg_lo:[0,1] neg_hi:[0,1]
	v_pk_add_f32 v[98:99], v[98:99], v[80:81] op_sel_hi:[1,0] neg_lo:[0,1] neg_hi:[0,1]
	v_pk_add_f32 v[100:101], v[100:101], v[80:81] op_sel_hi:[1,0] neg_lo:[0,1] neg_hi:[0,1]
	v_mul_f32_e32 v112, v112, v82
	v_pk_add_f32 v[102:103], v[102:103], v[80:81] op_sel_hi:[1,0] neg_lo:[0,1] neg_hi:[0,1]
	v_pk_add_f32 v[104:105], v[104:105], v[80:81] op_sel_hi:[1,0] neg_lo:[0,1] neg_hi:[0,1]
	v_pk_add_f32 v[106:107], v[106:107], v[80:81] op_sel_hi:[1,0] neg_lo:[0,1] neg_hi:[0,1]
	v_pk_add_f32 v[108:109], v[108:109], v[80:81] op_sel_hi:[1,0] neg_lo:[0,1] neg_hi:[0,1]
	v_sub_f32_e32 v79, v79, v80
	v_sub_f32_e32 v78, v78, v80
	v_sub_f32_e32 v77, v77, v80
	v_sub_f32_e32 v76, v76, v80
	v_sub_f32_e32 v75, v75, v80
	v_sub_f32_e32 v74, v74, v80
	v_sub_f32_e32 v73, v73, v80
	v_sub_f32_e32 v72, v72, v80
	v_sub_f32_e32 v71, v71, v80
	v_sub_f32_e32 v70, v70, v80
	v_sub_f32_e32 v69, v69, v80
	v_sub_f32_e32 v68, v68, v80
	v_sub_f32_e32 v67, v67, v80
	v_sub_f32_e32 v66, v66, v80
	v_sub_f32_e32 v65, v65, v80
	v_sub_f32_e32 v64, v64, v80
	v_pk_add_f32 v[110:111], v[110:111], v[80:81] op_sel_hi:[1,0] neg_lo:[0,1] neg_hi:[0,1]
	v_pk_mul_f32 v[62:63], v[62:63], v[82:83] op_sel_hi:[1,0]
	v_pk_mul_f32 v[60:61], v[60:61], v[82:83] op_sel_hi:[1,0]
	v_pk_mul_f32 v[58:59], v[58:59], v[82:83] op_sel_hi:[1,0]
	v_pk_mul_f32 v[56:57], v[56:57], v[82:83] op_sel_hi:[1,0]
	v_pk_mul_f32 v[54:55], v[54:55], v[82:83] op_sel_hi:[1,0]
	v_pk_mul_f32 v[52:53], v[52:53], v[82:83] op_sel_hi:[1,0]
	v_pk_mul_f32 v[50:51], v[50:51], v[82:83] op_sel_hi:[1,0]
	v_pk_mul_f32 v[48:49], v[48:49], v[82:83] op_sel_hi:[1,0]
	v_pk_mul_f32 v[46:47], v[46:47], v[82:83] op_sel_hi:[1,0]
	v_pk_mul_f32 v[44:45], v[44:45], v[82:83] op_sel_hi:[1,0]
	v_pk_mul_f32 v[42:43], v[42:43], v[82:83] op_sel_hi:[1,0]
	v_pk_mul_f32 v[40:41], v[40:41], v[82:83] op_sel_hi:[1,0]
	v_pk_mul_f32 v[38:39], v[38:39], v[82:83] op_sel_hi:[1,0]
	v_pk_mul_f32 v[36:37], v[36:37], v[82:83] op_sel_hi:[1,0]
	v_pk_mul_f32 v[34:35], v[34:35], v[82:83] op_sel_hi:[1,0]
	v_pk_mul_f32 v[32:33], v[32:33], v[82:83] op_sel_hi:[1,0]
	v_pk_mul_f32 v[30:31], v[30:31], v[82:83] op_sel_hi:[1,0]
	v_pk_mul_f32 v[28:29], v[28:29], v[82:83] op_sel_hi:[1,0]
	v_pk_mul_f32 v[26:27], v[26:27], v[82:83] op_sel_hi:[1,0]
	v_pk_mul_f32 v[24:25], v[24:25], v[82:83] op_sel_hi:[1,0]
	v_pk_mul_f32 v[22:23], v[22:23], v[82:83] op_sel_hi:[1,0]
	v_pk_mul_f32 v[20:21], v[20:21], v[82:83] op_sel_hi:[1,0]
	v_pk_mul_f32 v[18:19], v[18:19], v[82:83] op_sel_hi:[1,0]
	v_pk_mul_f32 v[16:17], v[16:17], v[82:83] op_sel_hi:[1,0]
	v_pk_mul_f32 v[14:15], v[14:15], v[82:83] op_sel_hi:[1,0]
	v_pk_mul_f32 v[12:13], v[12:13], v[82:83] op_sel_hi:[1,0]
	v_pk_mul_f32 v[10:11], v[10:11], v[82:83] op_sel_hi:[1,0]
	v_pk_mul_f32 v[8:9], v[8:9], v[82:83] op_sel_hi:[1,0]
	v_pk_mul_f32 v[6:7], v[6:7], v[82:83] op_sel_hi:[1,0]
	v_pk_mul_f32 v[4:5], v[4:5], v[82:83] op_sel_hi:[1,0]
	v_pk_mul_f32 v[2:3], v[2:3], v[82:83] op_sel_hi:[1,0]
	v_pk_mul_f32 v[0:1], v[0:1], v[82:83] op_sel_hi:[1,0]
.LBB0_869:
	v_exp_f32_e32 v96, v96
	v_exp_f32_e32 v97, v97
	v_exp_f32_e32 v98, v98
	v_mfma_f32_32x32x16_bf16 v[80:95], v[248:251], v[144:147], v[64:79]
	ds_read_b128 v[244:247], v220 offset:40960
	v_exp_f32_e32 v99, v99
	v_exp_f32_e32 v100, v100
	v_exp_f32_e32 v101, v101
	v_exp_f32_e32 v102, v102
	v_exp_f32_e32 v103, v103
	v_cvt_pk_bf16_f32 v122, v96, v97
	v_cvt_pk_bf16_f32 v123, v98, v99
	v_mfma_f32_32x32x16_bf16 v[80:95], v[252:255], v[156:159], v[80:95]
	ds_read_b128 v[248:251], v221 offset:40960
	s_add_i32 s4, s8, 4
	s_cmp_ge_u32 s4, s9
	s_cbranch_scc1 .Lmla_dma_skip_t2
	s_add_u32 s98, s34, s60
	s_addc_u32 s99, s35, s59
	s_add_u32 s98, s98, 0x14108000
	s_addc_u32 s99, s99, 0
	s_add_u32 s100, s34, s62
	s_addc_u32 s101, s35, s61
	s_add_u32 s100, s100, 0x171b0200
	s_addc_u32 s101, s101, 0
	s_mov_b32 m0, s46
	s_cmp_lg_u64 s[24:25], 0
	s_cselect_b32 s4, s100, s98
	s_cselect_b32 s5, s101, s99
	global_load_lds_dwordx4 v190, s[4:5]
	s_mov_b32 m0, s47
	s_cmp_lg_u64 s[26:27], 0
	s_cselect_b32 s4, s100, s98
	s_cselect_b32 s5, s101, s99
	global_load_lds_dwordx4 v192, s[4:5]
	s_mov_b32 m0, s48
	s_cmp_lg_u64 s[28:29], 0
	s_cselect_b32 s4, s100, s98
	s_cselect_b32 s5, s101, s99
	global_load_lds_dwordx4 v194, s[4:5]
	s_mov_b32 m0, s49
	s_cmp_lg_u64 s[30:31], 0
	s_cselect_b32 s4, s100, s98
	s_cselect_b32 s5, s101, s99
	global_load_lds_dwordx4 v196, s[4:5]
	s_mov_b32 m0, s50
	s_cmp_lg_u64 s[6:7], 0
	s_cselect_b32 s4, s100, s98
	s_cselect_b32 s5, s101, s99
	global_load_lds_dwordx4 v198, s[4:5]
.Lmla_dma_skip_t2:
	v_cvt_pk_bf16_f32 v124, v100, v101
	v_cvt_pk_bf16_f32 v125, v102, v103
	v_exp_f32_e32 v104, v104
	v_exp_f32_e32 v105, v105
	v_exp_f32_e32 v106, v106
	v_exp_f32_e32 v107, v107
	v_mfma_f32_32x32x16_bf16 v[80:95], v[176:179], v[168:171], v[80:95]
	ds_read_b128 v[252:255], v206 offset:20480
	v_exp_f32_e32 v108, v108
	v_exp_f32_e32 v109, v109
	v_exp_f32_e32 v110, v110
	v_exp_f32_e32 v111, v111
	s_add_i32 s4, s8, 4
	s_cmp_ge_u32 s4, s9
	s_waitcnt lgkmcnt(5)
	v_mfma_f32_32x32x16_bf16 v[80:95], v[180:183], v[172:175], v[80:95]
	ds_read_b128 v[176:179], v208 offset:20480
	s_waitcnt lgkmcnt(5)
	v_mfma_f32_32x32x16_bf16 v[80:95], v[236:239], v[164:167], v[80:95]
	ds_read_b128 v[180:183], v210 offset:20480
	s_waitcnt lgkmcnt(5)
	v_mfma_f32_32x32x16_bf16 v[80:95], v[240:243], v[160:163], v[80:95]
	ds_read_b128 v[236:239], v212 offset:20480
	s_waitcnt lgkmcnt(5)
	v_mfma_f32_32x32x16_bf16 v[80:95], v[244:247], v[152:155], v[80:95]
	ds_read_b128 v[240:243], v225 offset:32768
	s_waitcnt lgkmcnt(5)
	v_mfma_f32_32x32x16_bf16 v[80:95], v[248:251], v[148:151], v[80:95]
	ds_read_b128 v[244:247], v225 offset:36864
	s_waitcnt lgkmcnt(5)
	v_mfma_f32_32x32x16_bf16 v[80:95], v[252:255], v[140:143], v[80:95]
	ds_read_b128 v[248:251], v225 offset:40960
	s_waitcnt lgkmcnt(5)
	v_mfma_f32_32x32x16_bf16 v[80:95], v[176:179], v[136:139], v[80:95]
	ds_read_b128 v[252:255], v225 offset:45056
	s_waitcnt lgkmcnt(5)
	v_mfma_f32_32x32x16_bf16 v[80:95], v[180:183], v[132:135], v[80:95]
	ds_read_b128 v[176:179], v226 offset:32768
	s_waitcnt lgkmcnt(5)
	v_mfma_f32_32x32x16_bf16 v[80:95], v[236:239], v[128:131], v[80:95]
	ds_read_b128 v[180:183], v226 offset:36864
	s_waitcnt lgkmcnt(5)
	v_mfma_f32_32x32x16_bf16 v[48:63], v[240:243], v[122:125], v[48:63]
	ds_read_b128 v[236:239], v226 offset:40960
	s_nop 8
	v_max_f32_e32 v113, v81, v81
	v_max_f32_e32 v126, v80, v80
	v_max_f32_e32 v113, v126, v113
	v_max3_f32 v113, v113, v82, v83
	v_max3_f32 v113, v113, v84, v85
	v_max3_f32 v113, v113, v86, v87
	v_max3_f32 v113, v113, v88, v89
	s_waitcnt lgkmcnt(5)
	v_mfma_f32_32x32x16_bf16 v[32:47], v[244:247], v[122:125], v[32:47]
	ds_read_b128 v[240:243], v226 offset:45056
	v_max3_f32 v113, v113, v90, v91
	v_max3_f32 v113, v113, v92, v93
	v_max3_f32 v113, v113, v94, v95
	s_waitcnt lgkmcnt(5)
	v_mfma_f32_32x32x16_bf16 v[16:31], v[248:251], v[122:125], v[16:31]
	ds_read_b128 v[244:247], v214
	s_waitcnt lgkmcnt(5)
	v_mfma_f32_32x32x16_bf16 v[0:15], v[252:255], v[122:125], v[0:15]
	ds_read_b128 v[248:251], v215
	v_cvt_pk_bf16_f32 v118, v104, v105
	v_cvt_pk_bf16_f32 v119, v106, v107
	v_cvt_pk_bf16_f32 v120, v108, v109
	v_cvt_pk_bf16_f32 v121, v110, v111
	s_nop 0
	s_waitcnt lgkmcnt(5)
	v_mfma_f32_32x32x16_bf16 v[48:63], v[176:179], v[118:121], v[48:63]
	ds_read_b128 v[252:255], v216
	s_waitcnt lgkmcnt(5)
	v_mfma_f32_32x32x16_bf16 v[32:47], v[180:183], v[118:121], v[32:47]
	ds_read_b128 v[176:179], v217
	s_waitcnt lgkmcnt(5)
	v_mfma_f32_32x32x16_bf16 v[16:31], v[236:239], v[118:121], v[16:31]
	ds_read_b128 v[180:183], v218
	ds_bpermute_b32 v114, v229, v113
	s_waitcnt lgkmcnt(6)
	v_mfma_f32_32x32x16_bf16 v[0:15], v[240:243], v[118:121], v[0:15]
	ds_read_b128 v[236:239], v219

.LBB0_873:
	v_exp_f32_e32 v113, v80
	v_exp_f32_e32 v126, v85
	v_exp_f32_e32 v127, v86
	v_mfma_f32_32x32x16_bf16 v[96:111], v[244:247], v[144:147], v[64:79]
	ds_read_b128 v[240:243], v220
	v_add_f32_e32 v231, 0, v113
	v_exp_f32_e32 v230, v87
	v_exp_f32_e32 v88, v88
	v_exp_f32_e32 v89, v89
	v_exp_f32_e32 v90, v90
	v_exp_f32_e32 v91, v91
	v_exp_f32_e32 v92, v92
	v_mfma_f32_32x32x16_bf16 v[96:111], v[248:251], v[156:159], v[96:111]
	ds_read_b128 v[244:247], v221
	v_exp_f32_e32 v93, v93
	s_add_u32 s62, s62, 0x180
	s_addc_u32 s61, s61, 0
	s_add_u32 s60, s60, 0x12000
	s_addc_u32 s59, s59, 0
	s_add_i32 s4, s16, 3
	v_mfma_f32_32x32x16_bf16 v[96:111], v[252:255], v[168:171], v[96:111]
	ds_read_b128 v[248:251], v206
	s_cmp_le_u32 s4, s9
	v_mfma_f32_32x32x16_bf16 v[96:111], v[176:179], v[172:175], v[96:111]
	ds_read_b128 v[252:255], v208
	v_mfma_f32_32x32x16_bf16 v[96:111], v[180:183], v[164:167], v[96:111]
	ds_read_b128 v[176:179], v210
	s_waitcnt lgkmcnt(5)
	v_mfma_f32_32x32x16_bf16 v[96:111], v[236:239], v[160:163], v[96:111]
	ds_read_b128 v[180:183], v212
	s_waitcnt lgkmcnt(5)
	v_mfma_f32_32x32x16_bf16 v[96:111], v[240:243], v[152:155], v[96:111]
	ds_read_b128 v[236:239], v227 offset:32768
	s_waitcnt lgkmcnt(5)
	v_mfma_f32_32x32x16_bf16 v[96:111], v[244:247], v[148:151], v[96:111]
	ds_read_b128 v[240:243], v227 offset:36864
	s_waitcnt lgkmcnt(5)
	v_mfma_f32_32x32x16_bf16 v[96:111], v[248:251], v[140:143], v[96:111]
	ds_read_b128 v[244:247], v227 offset:40960
	s_waitcnt lgkmcnt(5)
	v_mfma_f32_32x32x16_bf16 v[96:111], v[252:255], v[136:139], v[96:111]
	ds_read_b128 v[248:251], v227 offset:45056
	v_exp_f32_e32 v118, v81
	v_exp_f32_e32 v119, v82
	v_exp_f32_e32 v120, v83
	v_exp_f32_e32 v121, v84
	s_waitcnt lgkmcnt(5)
	v_mfma_f32_32x32x16_bf16 v[96:111], v[176:179], v[132:135], v[96:111]
	ds_read_b128 v[252:255], v228 offset:36864
	v_cvt_pk_bf16_f32 v114, v113, v118
	v_add_f32_e32 v113, v118, v231
	v_add_f32_e32 v113, v119, v113
	v_add_f32_e32 v113, v120, v113
	v_add_f32_e32 v113, v121, v113
	v_cvt_pk_bf16_f32 v115, v119, v120
	v_cvt_pk_bf16_f32 v116, v121, v126
	v_cvt_pk_bf16_f32 v117, v127, v230
	v_add_f32_e32 v113, v126, v113
	s_waitcnt lgkmcnt(5)
	v_mfma_f32_32x32x16_bf16 v[96:111], v[180:183], v[128:131], v[96:111]
	ds_read_b128 v[176:179], v228 offset:32768
	v_exp_f32_e32 v118, v94
	v_exp_f32_e32 v119, v95
	s_waitcnt lgkmcnt(5)
	v_mfma_f32_32x32x16_bf16 v[48:63], v[236:239], v[114:117], v[48:63]
	ds_read_b128 v[180:183], v228 offset:40960
	v_add_f32_e32 v80, v127, v113
	v_add_f32_e32 v80, v230, v80
	v_add_f32_e32 v113, v88, v80
	v_cvt_pk_bf16_f32 v88, v88, v89
	s_waitcnt lgkmcnt(5)
	v_mfma_f32_32x32x16_bf16 v[32:47], v[240:243], v[114:117], v[32:47]
	ds_read_b128 v[236:239], v228 offset:45056
	v_add_f32_e32 v84, v89, v113
	v_add_f32_e32 v84, v90, v84
	v_add_f32_e32 v84, v91, v84
	v_add_f32_e32 v113, v92, v84
	v_add_f32_e32 v113, v93, v113
	v_cvt_pk_bf16_f32 v89, v90, v91
	s_waitcnt lgkmcnt(5)
	v_mfma_f32_32x32x16_bf16 v[16:31], v[244:247], v[114:117], v[16:31]
	v_cvt_pk_bf16_f32 v90, v92, v93
	v_cvt_pk_bf16_f32 v91, v118, v119
	s_waitcnt lgkmcnt(4)
	v_mfma_f32_32x32x16_bf16 v[0:15], v[248:251], v[114:117], v[0:15]
	v_max_f32_e32 v114, v97, v97
	v_max_f32_e32 v115, v96, v96
	v_max_f32_e32 v114, v115, v114
	v_max3_f32 v114, v114, v98, v99
	s_waitcnt lgkmcnt(3)
	v_mfma_f32_32x32x16_bf16 v[32:47], v[252:255], v[88:91], v[32:47]
	s_waitcnt vmcnt(0)
	s_barrier
	s_waitcnt lgkmcnt(2)
	v_mfma_f32_32x32x16_bf16 v[48:63], v[176:179], v[88:91], v[48:63]
	v_max3_f32 v80, v114, v100, v101
	v_max3_f32 v80, v80, v102, v103
	v_max3_f32 v80, v80, v104, v105
	v_max3_f32 v80, v80, v106, v107
	v_max3_f32 v80, v80, v108, v109
	v_max3_f32 v80, v80, v110, v111
	ds_bpermute_b32 v81, v229, v80
	s_waitcnt lgkmcnt(2)
	v_mfma_f32_32x32x16_bf16 v[16:31], v[180:183], v[88:91], v[16:31]
	v_add_f32_e32 v82, v118, v113
	v_add_f32_e32 v82, v119, v82
	v_add_f32_e32 v230, v112, v82
	s_waitcnt lgkmcnt(0)
	v_max_f32_e32 v81, v81, v81
	v_max_f32_e32 v82, v80, v81
	v_mfma_f32_32x32x16_bf16 v[0:15], v[236:239], v[88:91], v[0:15]
	s_cbranch_scc0 .LBB0_875
	s_mov_b32 s8, s16
	v_cmp_lt_f32_e32 vcc, 0, v82
	s_cbranch_vccnz .LBB0_858
	s_branch .LBB0_859
